# static s_setprio 1 for waves 4-7 through the item phases (P2, P4, P7)
# speedup vs baseline: 1.0018x; 1.0018x over previous
.LBB0_536:
	v_readfirstlane_b32 s0, v202
	s_cmpk_lt_u32 s0, 0x100
	s_cbranch_scc1 .Lprio_p2
	s_setprio 1

.LBB0_717:
	v_readfirstlane_b32 s4, v202
	s_cmpk_lt_u32 s4, 0x100
	s_cbranch_scc1 .Lprio_p4
	s_setprio 1
